# attention QK/PV LDS fragment reads software-pipelined (counted lgkmcnt) + norm/a_low pipelining + gemm1 sc1 stores
# speedup vs baseline: 1.0261x; 1.0051x over previous
; #define LAS __attribute__((address_space(3)))
; __device__ __forceinline__ void attn_item(const Params& P, int half, int item, LAS unsigned char* lds, unsigned* ctr) {
;     ...
;     const int m0 = (16 * w < 96) ? 16 * w : 96;
;     f32x4 S[10];
; #pragma unroll
;     for (int jt = 0; jt < 10; ++jt) {
;         S[jt] = (f32x4){0.f, 0.f, 0.f, 0.f};
;         const LAS unsigned char* kr = Ks + (m0 + jt * 16 + c) * KSTR + 16 * g;
; #pragma unroll
;         for (int ks = 0; ks < 4; ++ks) { const bf16x8 a = *(const LAS bf16x8*)(kr + ks * 64); S[jt] = __builtin_amdgcn_mfma_f32_16x16x32_bf16(a, Qf[ks], S[jt], 0, 0, 0); }
;     }
.LBB0_539:
	s_or_b64 exec, exec, s[30:31]
	s_and_b32 s6, s6, -16
	v_and_b32_e32 v54, 15, v137
	s_min_i32 s6, s6, 0x60
	v_or_b32_e32 v18, s6, v54
	s_movk_i32 s7, 0x110
	v_mul_lo_u32 v18, v18, s7
	v_add3_u32 v55, 0, v194, v18
	ds_read_b128 v[204:207], v55
	ds_read_b128 v[208:211], v55 offset:64
	ds_read_b128 v[212:215], v55 offset:4416
	ds_read_b128 v[216:219], v55 offset:8768
	ds_read_b128 v[220:223], v55 offset:13120
	ds_read_b128 v[224:227], v55 offset:128
	s_and_b32 s5, s5, 0xff
	s_cmp_eq_u32 s5, 0
	s_cselect_b64 vcc, -1, 0
	s_mov_b32 s5, 0xff800000
	v_lshlrev_b32_e32 v194, 3, v136
	s_waitcnt lgkmcnt(5)
	v_mfma_f32_16x16x32_bf16 v[18:21], v[204:207], v[6:9], 0
	ds_read_b128 v[204:207], v55 offset:17472
	ds_read_b128 v[236:239], v55 offset:21824
	ds_read_b128 v[240:243], v55 offset:192
	s_waitcnt lgkmcnt(7)
	v_mfma_f32_16x16x32_bf16 v[18:21], v[208:211], v[14:17], v[18:21]
	ds_read_b128 v[208:211], v55 offset:26176
	ds_read_b128 v[244:247], v55 offset:30528
	ds_read_b128 v[176:179], v55 offset:4352
	s_waitcnt lgkmcnt(6)
	v_mfma_f32_16x16x32_bf16 v[18:21], v[224:227], v[2:5], v[18:21]
	ds_read_b128 v[224:227], v55 offset:34880
	ds_read_b128 v[180:183], v55 offset:4480
	ds_read_b128 v[184:187], v55 offset:4544
	s_waitcnt lgkmcnt(6)
	v_mfma_f32_16x16x32_bf16 v[18:21], v[240:243], v[10:13], v[18:21]
	ds_read_b128 v[240:243], v55 offset:8704
	ds_read_b128 v[188:191], v55 offset:8832
	s_waitcnt lgkmcnt(5)
	v_mfma_f32_16x16x32_bf16 v[22:25], v[176:179], v[6:9], 0
	v_mfma_f32_16x16x32_bf16 v[22:25], v[212:215], v[14:17], v[22:25]
	ds_read_b128 v[212:215], v55 offset:8896
	s_waitcnt lgkmcnt(4)
	v_mfma_f32_16x16x32_bf16 v[22:25], v[180:183], v[2:5], v[22:25]
	ds_read_b128 v[176:179], v55 offset:13056
	s_waitcnt lgkmcnt(4)
	v_mfma_f32_16x16x32_bf16 v[22:25], v[184:187], v[10:13], v[22:25]
	ds_read_b128 v[180:183], v55 offset:13184
	s_waitcnt lgkmcnt(4)
	v_mfma_f32_16x16x32_bf16 v[26:29], v[240:243], v[6:9], 0
	v_mfma_f32_16x16x32_bf16 v[26:29], v[216:219], v[14:17], v[26:29]
	ds_read_b128 v[216:219], v55 offset:13248
	s_waitcnt lgkmcnt(4)
	v_mfma_f32_16x16x32_bf16 v[26:29], v[188:191], v[2:5], v[26:29]
	ds_read_b128 v[240:243], v55 offset:17408
	s_waitcnt lgkmcnt(4)
	v_mfma_f32_16x16x32_bf16 v[26:29], v[212:215], v[10:13], v[26:29]
	ds_read_b128 v[212:215], v55 offset:17536
	s_waitcnt lgkmcnt(4)
	v_mfma_f32_16x16x32_bf16 v[30:33], v[176:179], v[6:9], 0
	v_mfma_f32_16x16x32_bf16 v[30:33], v[220:223], v[14:17], v[30:33]
	ds_read_b128 v[220:223], v55 offset:17600
	s_waitcnt lgkmcnt(4)
	v_mfma_f32_16x16x32_bf16 v[30:33], v[180:183], v[2:5], v[30:33]
	ds_read_b128 v[176:179], v55 offset:21760
	s_waitcnt lgkmcnt(4)
	v_mfma_f32_16x16x32_bf16 v[30:33], v[216:219], v[10:13], v[30:33]
	ds_read_b128 v[216:219], v55 offset:21888
	s_waitcnt lgkmcnt(4)
	v_mfma_f32_16x16x32_bf16 v[34:37], v[240:243], v[6:9], 0
	v_mfma_f32_16x16x32_bf16 v[34:37], v[204:207], v[14:17], v[34:37]
	ds_read_b128 v[204:207], v55 offset:21952
	s_waitcnt lgkmcnt(4)
	v_mfma_f32_16x16x32_bf16 v[34:37], v[212:215], v[2:5], v[34:37]
	ds_read_b128 v[212:215], v55 offset:26112
	s_waitcnt lgkmcnt(4)
	v_mfma_f32_16x16x32_bf16 v[34:37], v[220:223], v[10:13], v[34:37]
	ds_read_b128 v[220:223], v55 offset:26240
	s_waitcnt lgkmcnt(4)
	v_mfma_f32_16x16x32_bf16 v[38:41], v[176:179], v[6:9], 0
	v_mfma_f32_16x16x32_bf16 v[38:41], v[236:239], v[14:17], v[38:41]
	ds_read_b128 v[236:239], v55 offset:26304
	s_waitcnt lgkmcnt(4)
	v_mfma_f32_16x16x32_bf16 v[38:41], v[216:219], v[2:5], v[38:41]
	ds_read_b128 v[216:219], v55 offset:30464
	s_waitcnt lgkmcnt(4)
	v_mfma_f32_16x16x32_bf16 v[38:41], v[204:207], v[10:13], v[38:41]
	ds_read_b128 v[204:207], v55 offset:30592
	s_waitcnt lgkmcnt(4)
	v_mfma_f32_16x16x32_bf16 v[42:45], v[212:215], v[6:9], 0
	v_mfma_f32_16x16x32_bf16 v[42:45], v[208:211], v[14:17], v[42:45]
	ds_read_b128 v[208:211], v55 offset:30656
	s_waitcnt lgkmcnt(4)
	v_mfma_f32_16x16x32_bf16 v[42:45], v[220:223], v[2:5], v[42:45]
	ds_read_b128 v[212:215], v55 offset:34816
	s_waitcnt lgkmcnt(4)
	v_mfma_f32_16x16x32_bf16 v[42:45], v[236:239], v[10:13], v[42:45]
	ds_read_b128 v[220:223], v55 offset:34944
	s_waitcnt lgkmcnt(4)
	v_mfma_f32_16x16x32_bf16 v[46:49], v[216:219], v[6:9], 0
	v_mfma_f32_16x16x32_bf16 v[46:49], v[244:247], v[14:17], v[46:49]
	ds_read_b128 v[216:219], v55 offset:35008
	s_waitcnt lgkmcnt(4)
	v_mfma_f32_16x16x32_bf16 v[46:49], v[204:207], v[2:5], v[46:49]
	ds_read_b128 v[204:207], v55 offset:39168
	s_waitcnt lgkmcnt(4)
	v_mfma_f32_16x16x32_bf16 v[46:49], v[208:211], v[10:13], v[46:49]
	ds_read_b128 v[208:211], v55 offset:39232
	s_waitcnt lgkmcnt(4)
	v_mfma_f32_16x16x32_bf16 v[50:53], v[212:215], v[6:9], 0
	v_mfma_f32_16x16x32_bf16 v[50:53], v[224:227], v[14:17], v[50:53]
	ds_read_b128 v[212:215], v55 offset:39296
	s_waitcnt lgkmcnt(4)
	v_mfma_f32_16x16x32_bf16 v[50:53], v[220:223], v[2:5], v[50:53]
	ds_read_b128 v[220:223], v55 offset:39360
	s_waitcnt lgkmcnt(4)
	v_mfma_f32_16x16x32_bf16 v[50:53], v[216:219], v[10:13], v[50:53]
	s_nop 0
	s_waitcnt lgkmcnt(3)
	v_mfma_f32_16x16x32_bf16 v[6:9], v[204:207], v[6:9], 0
	s_nop 0
	s_waitcnt lgkmcnt(2)
	v_mfma_f32_16x16x32_bf16 v[6:9], v[208:211], v[14:17], v[6:9]
	s_nop 0
	s_waitcnt lgkmcnt(1)
	v_mfma_f32_16x16x32_bf16 v[2:5], v[212:215], v[2:5], v[6:9]
	s_nop 4
	s_nop 0
	s_waitcnt lgkmcnt(0)
; #define LAS __attribute__((address_space(3)))
; __device__ __forceinline__ void attn_item(const Params& P, int half, int item, LAS unsigned char* lds, unsigned* ctr) {
;     ...
;         for (int ks = 0; ks < 4; ++ks) { const bf16x8 a = *(const LAS bf16x8*)(kr + ks * 64); S[jt] = __builtin_amdgcn_mfma_f32_16x16x32_bf16(a, Qf[ks], S[jt], 0, 0, 0); }
;     }
;     float mx = -INFINITY;
;     const int dbase = qi + 128 - m0 - 4 * g;
;     const unsigned dlim = (unsigned)((n == 0) ? (qi < 128 ? qi : 128) : 128);
; #pragma unroll
;     for (int jt = 0; jt < 10; ++jt)
; #pragma unroll
;         for (int jj = 0; jj < 4; ++jj) { const bool ok = (unsigned)(dbase - (jt * 16 + jj)) <= dlim;
;             const float s = ok ? S[jt][jj] : -INFINITY; S[jt][jj] = s; mx = fmaxf(mx, s); }
;     mx = fmaxf(mx, __shfl_xor(mx, 16)); mx = fmaxf(mx, __shfl_xor(mx, 32));
	v_mfma_f32_16x16x32_bf16 v[2:5], v[220:223], v[10:13], v[2:5]
	v_lshlrev_b32_e32 v6, 2, v136
	v_min_i32_e32 v7, 0x80, v138
	v_mov_b32_e32 v8, 0x80
	v_or_b32_e32 v55, s6, v6
	v_cndmask_b32_e32 v7, v8, v7, vcc
	v_add_u32_e32 v8, 0x80, v138
	v_sub_u32_e32 v9, v8, v55
	v_bitop3_b32 v6, s6, v6, s6 bitop3:3
	v_cmp_le_u32_e32 vcc, v9, v7
	v_add_u32_e32 v8, v8, v6
	v_sub_u32_e32 v11, v138, v55
	v_cndmask_b32_e32 v9, v235, v18, vcc
	v_cmp_le_u32_e32 vcc, v8, v7
	v_add_u32_e32 v12, 0x7e, v11
	v_add_u32_e32 v13, 0x7d, v11
	v_cndmask_b32_e32 v8, v235, v19, vcc
	v_cmp_le_u32_e32 vcc, v12, v7
	v_add_u32_e32 v14, 0x70, v11
	v_add_u32_e32 v15, 0x6f, v11
	v_cndmask_b32_e32 v12, v235, v20, vcc
	v_cmp_le_u32_e32 vcc, v13, v7
	v_add_u32_e32 v16, 0x6e, v11
	v_add_u32_e32 v17, 0x6d, v11
	v_cndmask_b32_e32 v13, v235, v21, vcc
	v_cmp_le_u32_e32 vcc, v14, v7
	v_add_u32_e32 v18, 0x60, v11
	v_add_u32_e32 v19, 0x5f, v11
	v_cndmask_b32_e32 v14, v235, v22, vcc
	v_cmp_le_u32_e32 vcc, v15, v7
	v_add_u32_e32 v20, 0x5e, v11
	v_add_u32_e32 v21, 0x5d, v11
	v_cndmask_b32_e32 v15, v235, v23, vcc
	v_cmp_le_u32_e32 vcc, v16, v7
	v_add_u32_e32 v22, 0x50, v11
	v_add_u32_e32 v23, 0x4f, v11
	v_cndmask_b32_e32 v16, v235, v24, vcc
	v_cmp_le_u32_e32 vcc, v17, v7
	v_max3_f32 v10, v9, s5, v8
	v_max3_f32 v10, v10, v12, v13
	v_cndmask_b32_e32 v17, v235, v25, vcc
	v_cmp_le_u32_e32 vcc, v18, v7
	v_max3_f32 v10, v10, v14, v15
	v_max3_f32 v10, v10, v16, v17
	v_cndmask_b32_e32 v18, v235, v26, vcc
	v_cmp_le_u32_e32 vcc, v19, v7
	v_add_u32_e32 v6, v138, v6
	v_readlane_b32 s5, v255, 16
	v_cndmask_b32_e32 v19, v235, v27, vcc
	v_cmp_le_u32_e32 vcc, v20, v7
	v_max3_f32 v10, v10, v18, v19
	s_nop 0
	v_cndmask_b32_e32 v20, v235, v28, vcc
	v_cmp_le_u32_e32 vcc, v21, v7
	s_nop 1
	v_cndmask_b32_e32 v21, v235, v29, vcc
	v_cmp_le_u32_e32 vcc, v22, v7
	v_max3_f32 v10, v10, v20, v21
	s_nop 0
	v_cndmask_b32_e32 v22, v235, v30, vcc
	v_cmp_le_u32_e32 vcc, v23, v7
	v_add_u32_e32 v23, 0x4e, v11
	s_nop 0
	v_cndmask_b32_e32 v25, v235, v31, vcc
	v_cmp_le_u32_e32 vcc, v23, v7
	v_add_u32_e32 v23, 0x4d, v11
	v_max3_f32 v10, v10, v22, v25
	v_cndmask_b32_e32 v26, v235, v32, vcc
	v_cmp_le_u32_e32 vcc, v23, v7
	v_add_u32_e32 v23, 64, v11
	s_nop 0
	v_cndmask_b32_e32 v27, v235, v33, vcc
	v_cmp_le_u32_e32 vcc, v23, v7
	v_add_u32_e32 v23, 63, v11
	v_max3_f32 v10, v10, v26, v27
	v_cndmask_b32_e32 v28, v235, v34, vcc
	v_cmp_le_u32_e32 vcc, v23, v7
	v_add_u32_e32 v23, 62, v11
	s_nop 0
	v_cndmask_b32_e32 v29, v235, v35, vcc
	v_cmp_le_u32_e32 vcc, v23, v7
	v_add_u32_e32 v23, 61, v11
	v_max3_f32 v10, v10, v28, v29
	v_cndmask_b32_e32 v30, v235, v36, vcc
	v_cmp_le_u32_e32 vcc, v23, v7
	v_add_u32_e32 v23, 48, v11
	s_nop 0
	v_cndmask_b32_e32 v31, v235, v37, vcc
	v_cmp_le_u32_e32 vcc, v23, v7
	v_add_u32_e32 v23, 47, v11
	v_max3_f32 v10, v10, v30, v31
	v_cndmask_b32_e32 v34, v235, v38, vcc
	v_cmp_le_u32_e32 vcc, v23, v7
	v_add_u32_e32 v23, 46, v11
	s_nop 0
	v_cndmask_b32_e32 v35, v235, v39, vcc
	v_cmp_le_u32_e32 vcc, v23, v7
	v_add_u32_e32 v23, 45, v11
	v_max3_f32 v10, v10, v34, v35
	v_cndmask_b32_e32 v36, v235, v40, vcc
	v_cmp_le_u32_e32 vcc, v23, v7
	v_add_u32_e32 v23, 32, v11
	s_nop 0
	v_cndmask_b32_e32 v37, v235, v41, vcc
	v_cmp_le_u32_e32 vcc, v23, v7
	v_add_u32_e32 v23, 31, v11
	v_max3_f32 v10, v10, v36, v37
	v_cndmask_b32_e32 v38, v235, v42, vcc
	v_cmp_le_u32_e32 vcc, v23, v7
	v_add_u32_e32 v23, 30, v11
	s_nop 0
	v_cndmask_b32_e32 v39, v235, v43, vcc
	v_cmp_le_u32_e32 vcc, v23, v7
	v_add_u32_e32 v23, 29, v11
	v_max3_f32 v10, v10, v38, v39
	v_cndmask_b32_e32 v40, v235, v44, vcc
	v_cmp_le_u32_e32 vcc, v23, v7
	v_add_u32_e32 v23, 16, v11
	s_nop 0
	v_cndmask_b32_e32 v41, v235, v45, vcc
	v_cmp_le_u32_e32 vcc, v23, v7
	v_add_u32_e32 v23, 15, v11
	v_max3_f32 v10, v10, v40, v41
	v_cndmask_b32_e32 v42, v235, v46, vcc
	v_cmp_le_u32_e32 vcc, v23, v7
	v_add_u32_e32 v23, 14, v11
	s_nop 0
	v_cndmask_b32_e32 v43, v235, v47, vcc
	v_cmp_le_u32_e32 vcc, v23, v7
	v_add_u32_e32 v23, 13, v11
	v_max3_f32 v10, v10, v42, v43
	v_cndmask_b32_e32 v44, v235, v48, vcc
	v_cmp_le_u32_e32 vcc, v23, v7
	s_nop 1
	v_cndmask_b32_e32 v45, v235, v49, vcc
	v_cmp_le_u32_e32 vcc, v11, v7
	v_max3_f32 v10, v10, v44, v45
	s_nop 0
	v_cndmask_b32_e32 v46, v235, v50, vcc
	v_cmp_le_u32_e32 vcc, v6, v7
	s_nop 1
	v_cndmask_b32_e32 v47, v235, v51, vcc
	v_max3_f32 v6, v10, v46, v47
	v_add_u32_e32 v10, -2, v11
	v_cmp_le_u32_e32 vcc, v10, v7
	v_add_u32_e32 v10, -3, v11
	s_nop 0
	v_cndmask_b32_e32 v48, v235, v52, vcc
	v_cmp_le_u32_e32 vcc, v10, v7
	v_add_u32_e32 v10, -16, v11
	s_nop 0
	v_cndmask_b32_e32 v49, v235, v53, vcc
	v_cmp_le_u32_e32 vcc, v10, v7
	v_max3_f32 v6, v6, v48, v49
	s_nop 0
	v_cndmask_b32_e32 v50, v235, v2, vcc
	v_subrev_u32_e32 v2, 17, v11
	v_cmp_le_u32_e32 vcc, v2, v7
	s_nop 1
	v_cndmask_b32_e32 v51, v235, v3, vcc
	v_subrev_u32_e32 v3, 18, v11
	v_cmp_le_u32_e32 vcc, v3, v7
	v_subrev_u32_e32 v3, 19, v11
	v_max3_f32 v2, v6, v50, v51
	v_cndmask_b32_e32 v52, v235, v4, vcc
	v_and_b32_e32 v4, 64, v230
	v_cmp_le_u32_e32 vcc, v3, v7
	v_xor_b32_e32 v3, 16, v230
	v_add_u32_e32 v4, 64, v4
	v_cndmask_b32_e32 v53, v235, v5, vcc
	v_cmp_lt_i32_e32 vcc, v3, v4
	v_max3_f32 v2, v2, v52, v53
	s_nop 0
	v_cndmask_b32_e32 v3, v230, v3, vcc
	v_lshlrev_b32_e32 v56, 2, v3
	ds_bpermute_b32 v3, v56, v2
	s_waitcnt lgkmcnt(0)
	v_max_f32_e32 v3, v3, v3
	v_max_f32_e32 v2, v2, v3
	v_xor_b32_e32 v3, 32, v230
	v_cmp_lt_i32_e32 vcc, v3, v4
	s_nop 1
	v_cndmask_b32_e32 v3, v230, v3, vcc
	v_lshlrev_b32_e32 v57, 2, v3
	ds_bpermute_b32 v3, v57, v2
	s_waitcnt lgkmcnt(0)
; #define LAS __attribute__((address_space(3)))
; __device__ __forceinline__ unsigned cvt_pk_bf16(float lo, float hi) { unsigned r; asm volatile("v_cvt_pk_bf16_f32 %0, %1, %2" : "=v"(r) : "v"(lo), "v"(hi)); return r; }
; __device__ __forceinline__ void attn_item(const Params& P, int half, int item, LAS unsigned char* lds, unsigned* ctr) {
;     ...
;     float den = 0.f;
; #pragma unroll
;     for (int jt = 0; jt < 10; ++jt) { const f32x4 d = S[jt] - mx; f32x4 p; p[0] = __builtin_amdgcn_exp2f(d[0]); p[1] = __builtin_amdgcn_exp2f(d[1]); p[2] = __builtin_amdgcn_exp2f(d[2]); p[3] = __builtin_amdgcn_exp2f(d[3]);
;         S[jt] = p; den += (p[0] + p[1]) + (p[2] + p[3]); }
;     den += __shfl_xor(den, 16); den += __shfl_xor(den, 32);
;     bf16x8 Pf[5];
; #pragma unroll
;     for (int k5 = 0; k5 < 5; ++k5) { u32x4 pw; pw.x = cvt_pk_bf16(S[2 * k5][0], S[2 * k5][1]); pw.y = cvt_pk_bf16(S[2 * k5][2], S[2 * k5][3]); pw.z = cvt_pk_bf16(S[2 * k5 + 1][0], S[2 * k5 + 1][1]); pw.w = cvt_pk_bf16(S[2 * k5 + 1][2], S[2 * k5 + 1][3]); Pf[k5] = as_bf16x8(pw); }
;     const float inv = 1.0f / den;
;     bf16_t* op = Z + (size_t)qrow * ZC + colq + 4 * g;
; #pragma unroll
;     for (int dt = 0; dt < 8; ++dt) {
;         f32x4 O = (f32x4){0.f, 0.f, 0.f, 0.f};
;         const LAS unsigned char* vr = Vt + (dt * 16 + c) * VSTR + (m0 + 4 * g) * 2;
; #pragma unroll
;         for (int k5 = 0; k5 < 5; ++k5) { const u32x2 lo = *(const LAS u32x2*)(vr + k5 * 64), hi = *(const LAS u32x2*)(vr + k5 * 64 + 32);
;             const bf16x8 a = as_bf16x8((u32x4){lo.x, lo.y, hi.x, hi.y}); O = __builtin_amdgcn_mfma_f32_16x16x32_bf16(a, Pf[k5], O, 0, 0, 0); }
;         u32x2 ow; ow.x = cvt_pk_bf16(O[0] * inv, O[1] * inv); ow.y = cvt_pk_bf16(O[2] * inv, O[3] * inv);
;         *(u32x2*)(op + dt * 16) = ow;
	v_max_f32_e32 v3, v3, v3
	v_max_f32_e32 v24, v2, v3
	v_sub_f32_e32 v2, v13, v24
	v_sub_f32_e32 v3, v12, v24
	v_sub_f32_e32 v5, v8, v24
	v_sub_f32_e32 v4, v9, v24
	v_exp_f32_e32 v4, v4
	v_exp_f32_e32 v6, v5
	v_exp_f32_e32 v5, v3
	v_exp_f32_e32 v7, v2
	v_sub_f32_e32 v9, v16, v24
	v_sub_f32_e32 v10, v15, v24
	v_sub_f32_e32 v8, v14, v24
	v_pk_add_f32 v[2:3], v[4:5], v[6:7]
	v_exp_f32_e32 v8, v8
	v_add_f32_e32 v2, v2, v3
	v_add_f32_e32 v3, 0, v2
	v_sub_f32_e32 v2, v17, v24
	v_exp_f32_e32 v10, v10
	v_exp_f32_e32 v9, v9
	v_exp_f32_e32 v11, v2
	v_sub_f32_e32 v2, v21, v24
	v_sub_f32_e32 v14, v19, v24
	v_sub_f32_e32 v15, v18, v24
	v_pk_add_f32 v[12:13], v[8:9], v[10:11]
	v_exp_f32_e32 v58, v15
	v_pk_add_f32 v[12:13], v[12:13], v[12:13] op_sel_hi:[0,1]
	v_sub_f32_e32 v12, v20, v24
	v_exp_f32_e32 v59, v14
	v_exp_f32_e32 v60, v12
	v_exp_f32_e32 v61, v2
	v_sub_f32_e32 v2, v27, v24
	v_sub_f32_e32 v12, v26, v24
	v_sub_f32_e32 v14, v25, v24
	v_sub_f32_e32 v15, v22, v24
	v_exp_f32_e32 v16, v15
	v_exp_f32_e32 v22, v14
	v_exp_f32_e32 v12, v12
	v_exp_f32_e32 v2, v2
	v_add_f32_e32 v17, v58, v59
	v_add_f32_e32 v23, v60, v61
	v_pk_add_f32 v[14:15], v[16:17], v[22:23]
	v_pk_add_f32 v[18:19], v[12:13], v[2:3]
	v_sub_f32_e32 v3, v31, v24
	v_pk_add_f32 v[14:15], v[14:15], v[18:19]
	v_sub_f32_e32 v13, v30, v24
	v_pk_add_f32 v[26:27], v[14:15], v[14:15] op_sel_hi:[0,1]
	v_sub_f32_e32 v14, v29, v24
	v_sub_f32_e32 v15, v28, v24
	v_exp_f32_e32 v28, v15
	v_exp_f32_e32 v30, v14
	v_exp_f32_e32 v29, v13
	v_exp_f32_e32 v31, v3
	v_sub_f32_e32 v3, v37, v24
	v_sub_f32_e32 v13, v36, v24
	v_exp_f32_e32 v13, v13
	v_pk_add_f32 v[14:15], v[28:29], v[30:31]
	v_exp_f32_e32 v3, v3
	v_pk_add_f32 v[32:33], v[14:15], v[14:15] op_sel_hi:[0,1]
	v_sub_f32_e32 v14, v35, v24
	v_sub_f32_e32 v15, v34, v24
	v_exp_f32_e32 v23, v15
	v_exp_f32_e32 v25, v14
	v_sub_f32_e32 v14, v41, v24
	v_sub_f32_e32 v15, v40, v24
	v_sub_f32_e32 v17, v39, v24
	v_sub_f32_e32 v18, v38, v24
	v_exp_f32_e32 v34, v18
	v_exp_f32_e32 v36, v17
	v_exp_f32_e32 v32, v15
	v_exp_f32_e32 v26, v14
	v_add_f32_e32 v35, v23, v25
	v_add_f32_e32 v37, v13, v3
	v_pk_add_f32 v[14:15], v[34:35], v[36:37]
	v_pk_add_f32 v[18:19], v[32:33], v[26:27]
	v_sub_f32_e32 v17, v43, v24
	v_pk_add_f32 v[14:15], v[14:15], v[18:19]
	v_sub_f32_e32 v18, v42, v24
	v_pk_add_f32 v[38:39], v[14:15], v[14:15] op_sel_hi:[0,1]
	v_sub_f32_e32 v14, v45, v24
	v_sub_f32_e32 v15, v44, v24
	v_exp_f32_e32 v40, v18
	v_exp_f32_e32 v42, v17
	v_exp_f32_e32 v41, v15
	v_exp_f32_e32 v43, v14
	v_sub_f32_e32 v17, v47, v24
	v_sub_f32_e32 v18, v46, v24
	v_exp_f32_e32 v27, v18
	v_pk_add_f32 v[14:15], v[40:41], v[42:43]
	v_exp_f32_e32 v33, v17
	v_pk_add_f32 v[44:45], v[14:15], v[14:15] op_sel_hi:[0,1]
	v_sub_f32_e32 v14, v49, v24
	v_sub_f32_e32 v15, v48, v24
	v_exp_f32_e32 v35, v15
	v_exp_f32_e32 v37, v14
	v_sub_f32_e32 v14, v53, v24
	v_sub_f32_e32 v15, v52, v24
	v_sub_f32_e32 v17, v51, v24
	v_sub_f32_e32 v18, v50, v24
	v_exp_f32_e32 v46, v18
	v_exp_f32_e32 v48, v17
	v_exp_f32_e32 v44, v15
	v_exp_f32_e32 v38, v14
	v_add_f32_e32 v47, v27, v33
	v_add_f32_e32 v49, v35, v37
	v_pk_add_f32 v[14:15], v[46:47], v[48:49]
	v_pk_add_f32 v[18:19], v[44:45], v[38:39]
	s_nop 0
	v_pk_add_f32 v[14:15], v[14:15], v[18:19]
	v_cvt_pk_bf16_f32 v18, v4, v6
	v_cvt_pk_bf16_f32 v19, v5, v7
	v_cvt_pk_bf16_f32 v20, v8, v10
	v_cvt_pk_bf16_f32 v21, v9, v11
	s_nop 0
	v_add_f32_e32 v14, v14, v15
	ds_bpermute_b32 v15, v56, v14
	s_waitcnt lgkmcnt(0)
	v_add_f32_e32 v39, v14, v15
	ds_bpermute_b32 v45, v57, v39
	v_cvt_pk_bf16_f32 v14, v58, v59
	v_cvt_pk_bf16_f32 v15, v60, v61
	v_cvt_pk_bf16_f32 v16, v16, v22
	v_cvt_pk_bf16_f32 v17, v12, v2
	v_cvt_pk_bf16_f32 v10, v28, v30
	v_cvt_pk_bf16_f32 v11, v29, v31
	v_cvt_pk_bf16_f32 v12, v23, v25
	s_waitcnt lgkmcnt(0)
	v_add_f32_e32 v25, v39, v45
	v_div_scale_f32 v22, s[6:7], v25, v25, 1.0
	v_rcp_f32_e32 v23, v22
	v_cvt_pk_bf16_f32 v13, v13, v3
	v_cvt_pk_bf16_f32 v6, v34, v36
	v_cvt_pk_bf16_f32 v7, v32, v26
	v_cvt_pk_bf16_f32 v8, v40, v42
	v_cvt_pk_bf16_f32 v9, v41, v43
	s_nop 0
	v_fma_f32 v26, -v22, v23, 1.0
	v_fmac_f32_e32 v23, v26, v23
	v_div_scale_f32 v26, vcc, 1.0, v25, 1.0
	v_cvt_pk_bf16_f32 v2, v27, v33
	v_mul_f32_e32 v27, v26, v23
	v_fma_f32 v28, -v22, v27, v26
	v_fmac_f32_e32 v27, v28, v23
	v_fma_f32 v22, -v22, v27, v26
	v_div_fmas_f32 v22, v22, v23, v27
	v_lshlrev_b32_e32 v27, 1, v55
	v_mul_u32_u24_e32 v28, 0x210, v54
	v_add3_u32 v27, s5, v27, v28
	v_cvt_pk_bf16_f32 v3, v35, v37
	v_cvt_pk_bf16_f32 v4, v46, v48
	v_cvt_pk_bf16_f32 v5, v44, v38
	ds_read2_b64 v[204:207], v27 offset1:4
	ds_read2_b64 v[208:211], v27 offset0:8 offset1:12
	ds_read2_b64 v[212:215], v27 offset0:16 offset1:20
	ds_read2_b64 v[216:219], v27 offset0:24 offset1:28
	ds_read2_b64 v[220:223], v27 offset0:32 offset1:36
	s_nop 0
	s_waitcnt lgkmcnt(4)
	v_mfma_f32_16x16x32_bf16 v[28:31], v[204:207], v[18:21], 0
	v_div_fixup_f32 v26, v22, v25, 1.0
	v_lshl_add_u64 v[22:23], v[130:131], 0, v[194:195]
	v_add_u32_e32 v36, 0x2000, v27
	s_waitcnt lgkmcnt(3)
	v_mfma_f32_16x16x32_bf16 v[28:31], v[208:211], v[14:17], v[28:31]
	s_nop 0
	v_cmp_eq_u32_e32 vcc, 0, v136
	s_waitcnt lgkmcnt(2)
	v_mfma_f32_16x16x32_bf16 v[28:31], v[212:215], v[10:13], v[28:31]
	s_nop 0
	s_waitcnt lgkmcnt(1)
	v_mfma_f32_16x16x32_bf16 v[28:31], v[216:219], v[6:9], v[28:31]
	s_nop 0
	s_waitcnt lgkmcnt(0)
	v_mfma_f32_16x16x32_bf16 v[28:31], v[220:223], v[2:5], v[28:31]
	s_nop 7
	v_mul_f32_e32 v28, v26, v28
	v_mul_f32_e32 v29, v26, v29
	v_cvt_pk_bf16_f32 v28, v28, v29
	v_mul_f32_e32 v29, v26, v30
	v_mul_f32_e32 v30, v26, v31
	v_cvt_pk_bf16_f32 v29, v29, v30
	global_store_dwordx2 v[22:23], v[28:29], off
	ds_read2_b64 v[204:207], v36 offset0:32 offset1:36
	ds_read2_b64 v[208:211], v36 offset0:40 offset1:44
	ds_read2_b64 v[212:215], v36 offset0:48 offset1:52
	ds_read2_b64 v[216:219], v36 offset0:56 offset1:60
	ds_read2_b64 v[220:223], v36 offset0:64 offset1:68
	s_nop 0
	s_waitcnt lgkmcnt(4)
; #define LAS __attribute__((address_space(3)))
; __device__ __forceinline__ unsigned cvt_pk_bf16(float lo, float hi) { unsigned r; asm volatile("v_cvt_pk_bf16_f32 %0, %1, %2" : "=v"(r) : "v"(lo), "v"(hi)); return r; }
; __device__ __forceinline__ void attn_item(const Params& P, int half, int item, LAS unsigned char* lds, unsigned* ctr) {
;     ...
; #pragma unroll
;     for (int dt = 0; dt < 8; ++dt) {
;         f32x4 O = (f32x4){0.f, 0.f, 0.f, 0.f};
;         const LAS unsigned char* vr = Vt + (dt * 16 + c) * VSTR + (m0 + 4 * g) * 2;
; #pragma unroll
;         for (int k5 = 0; k5 < 5; ++k5) { const u32x2 lo = *(const LAS u32x2*)(vr + k5 * 64), hi = *(const LAS u32x2*)(vr + k5 * 64 + 32);
;             const bf16x8 a = as_bf16x8((u32x4){lo.x, lo.y, hi.x, hi.y}); O = __builtin_amdgcn_mfma_f32_16x16x32_bf16(a, Pf[k5], O, 0, 0, 0); }
;         u32x2 ow; ow.x = cvt_pk_bf16(O[0] * inv, O[1] * inv); ow.y = cvt_pk_bf16(O[2] * inv, O[3] * inv);
;         *(u32x2*)(op + dt * 16) = ow;
;     }
	v_mfma_f32_16x16x32_bf16 v[28:31], v[204:207], v[18:21], 0
	s_waitcnt lgkmcnt(3)
	v_mfma_f32_16x16x32_bf16 v[28:31], v[208:211], v[14:17], v[28:31]
	s_nop 0
	s_waitcnt lgkmcnt(2)
	v_mfma_f32_16x16x32_bf16 v[28:31], v[212:215], v[10:13], v[28:31]
	s_nop 0
	s_waitcnt lgkmcnt(1)
	v_mfma_f32_16x16x32_bf16 v[28:31], v[216:219], v[6:9], v[28:31]
	s_nop 0
	v_add_u32_e32 v36, 0x4000, v27
	s_waitcnt lgkmcnt(0)
	v_mfma_f32_16x16x32_bf16 v[28:31], v[220:223], v[2:5], v[28:31]
	s_nop 7
	v_mul_f32_e32 v28, v26, v28
	v_mul_f32_e32 v29, v26, v29
	v_cvt_pk_bf16_f32 v28, v28, v29
	v_mul_f32_e32 v29, v26, v30
	v_mul_f32_e32 v30, v26, v31
	v_cvt_pk_bf16_f32 v29, v29, v30
	global_store_dwordx2 v[22:23], v[28:29], off offset:32
	ds_read2_b64 v[204:207], v36 offset0:64 offset1:68
	ds_read2_b64 v[208:211], v36 offset0:72 offset1:76
	ds_read2_b64 v[212:215], v36 offset0:80 offset1:84
	ds_read2_b64 v[216:219], v36 offset0:88 offset1:92
	ds_read2_b64 v[220:223], v36 offset0:96 offset1:100
	s_nop 0
	s_waitcnt lgkmcnt(4)
	v_mfma_f32_16x16x32_bf16 v[28:31], v[204:207], v[18:21], 0
	s_waitcnt lgkmcnt(3)
	v_mfma_f32_16x16x32_bf16 v[28:31], v[208:211], v[14:17], v[28:31]
	s_nop 0
	s_waitcnt lgkmcnt(2)
	v_mfma_f32_16x16x32_bf16 v[28:31], v[212:215], v[10:13], v[28:31]
	s_nop 0
	s_waitcnt lgkmcnt(1)
	v_mfma_f32_16x16x32_bf16 v[28:31], v[216:219], v[6:9], v[28:31]
	s_nop 0
	v_add_u32_e32 v36, 0x6000, v27
	s_waitcnt lgkmcnt(0)
	v_mfma_f32_16x16x32_bf16 v[28:31], v[220:223], v[2:5], v[28:31]
	s_nop 7
	v_mul_f32_e32 v28, v26, v28
	v_mul_f32_e32 v29, v26, v29
	v_cvt_pk_bf16_f32 v28, v28, v29
	v_mul_f32_e32 v29, v26, v30
	v_mul_f32_e32 v30, v26, v31
	v_cvt_pk_bf16_f32 v29, v29, v30
	global_store_dwordx2 v[22:23], v[28:29], off offset:64
	ds_read2_b64 v[204:207], v36 offset0:96 offset1:100
	ds_read2_b64 v[208:211], v36 offset0:104 offset1:108
	ds_read2_b64 v[212:215], v36 offset0:112 offset1:116
	ds_read2_b64 v[216:219], v36 offset0:120 offset1:124
	ds_read2_b64 v[220:223], v36 offset0:128 offset1:132
	s_nop 0
	s_waitcnt lgkmcnt(4)
	v_mfma_f32_16x16x32_bf16 v[28:31], v[204:207], v[18:21], 0
	s_waitcnt lgkmcnt(3)
	v_mfma_f32_16x16x32_bf16 v[28:31], v[208:211], v[14:17], v[28:31]
	s_nop 0
	s_waitcnt lgkmcnt(2)
	v_mfma_f32_16x16x32_bf16 v[28:31], v[212:215], v[10:13], v[28:31]
	s_nop 0
	s_waitcnt lgkmcnt(1)
	v_mfma_f32_16x16x32_bf16 v[28:31], v[216:219], v[6:9], v[28:31]
	s_nop 0
	v_add_u32_e32 v36, 0x8000, v27
	s_waitcnt lgkmcnt(0)
	v_mfma_f32_16x16x32_bf16 v[28:31], v[220:223], v[2:5], v[28:31]
	s_nop 7
	v_mul_f32_e32 v28, v26, v28
	v_mul_f32_e32 v29, v26, v29
	v_cvt_pk_bf16_f32 v28, v28, v29
	v_mul_f32_e32 v29, v26, v30
	v_mul_f32_e32 v30, v26, v31
	v_cvt_pk_bf16_f32 v29, v29, v30
	global_store_dwordx2 v[22:23], v[28:29], off offset:96
	ds_read2_b64 v[204:207], v36 offset0:128 offset1:132
	ds_read2_b64 v[208:211], v36 offset0:136 offset1:140
	ds_read2_b64 v[212:215], v36 offset0:144 offset1:148
	ds_read2_b64 v[216:219], v36 offset0:152 offset1:156
	ds_read2_b64 v[220:223], v36 offset0:160 offset1:164
	s_nop 0
	s_waitcnt lgkmcnt(4)
	v_mfma_f32_16x16x32_bf16 v[28:31], v[204:207], v[18:21], 0
	s_waitcnt lgkmcnt(3)
	v_mfma_f32_16x16x32_bf16 v[28:31], v[208:211], v[14:17], v[28:31]
	s_nop 0
	s_waitcnt lgkmcnt(2)
	v_mfma_f32_16x16x32_bf16 v[28:31], v[212:215], v[10:13], v[28:31]
	s_nop 0
	s_waitcnt lgkmcnt(1)
	v_mfma_f32_16x16x32_bf16 v[28:31], v[216:219], v[6:9], v[28:31]
	s_nop 0
	v_add_u32_e32 v36, 0xa000, v27
	s_waitcnt lgkmcnt(0)
	v_mfma_f32_16x16x32_bf16 v[28:31], v[220:223], v[2:5], v[28:31]
	s_nop 7
	v_mul_f32_e32 v28, v26, v28
	v_mul_f32_e32 v29, v26, v29
	v_cvt_pk_bf16_f32 v28, v28, v29
	v_mul_f32_e32 v29, v26, v30
	v_mul_f32_e32 v30, v26, v31
	v_cvt_pk_bf16_f32 v29, v29, v30
	global_store_dwordx2 v[22:23], v[28:29], off offset:128
	ds_read2_b64 v[204:207], v36 offset0:160 offset1:164
	ds_read2_b64 v[208:211], v36 offset0:168 offset1:172
	ds_read2_b64 v[212:215], v36 offset0:176 offset1:180
	ds_read2_b64 v[216:219], v36 offset0:184 offset1:188
	ds_read2_b64 v[220:223], v36 offset0:192 offset1:196
	s_nop 0
	s_waitcnt lgkmcnt(4)
	v_mfma_f32_16x16x32_bf16 v[28:31], v[204:207], v[18:21], 0
	s_waitcnt lgkmcnt(3)
	v_mfma_f32_16x16x32_bf16 v[28:31], v[208:211], v[14:17], v[28:31]
	s_nop 0
	s_waitcnt lgkmcnt(2)
	v_mfma_f32_16x16x32_bf16 v[28:31], v[212:215], v[10:13], v[28:31]
	s_nop 0
	s_waitcnt lgkmcnt(1)
	v_mfma_f32_16x16x32_bf16 v[28:31], v[216:219], v[6:9], v[28:31]
	s_nop 0
	v_add_u32_e32 v36, 0xc000, v27
	s_waitcnt lgkmcnt(0)
	v_mfma_f32_16x16x32_bf16 v[28:31], v[220:223], v[2:5], v[28:31]
	s_nop 7
	v_mul_f32_e32 v28, v26, v28
	v_mul_f32_e32 v29, v26, v29
	v_cvt_pk_bf16_f32 v28, v28, v29
	v_mul_f32_e32 v29, v26, v30
	v_mul_f32_e32 v30, v26, v31
	v_cvt_pk_bf16_f32 v29, v29, v30
	global_store_dwordx2 v[22:23], v[28:29], off offset:160
	ds_read2_b64 v[204:207], v36 offset0:192 offset1:196
	ds_read2_b64 v[208:211], v36 offset0:200 offset1:204
	ds_read2_b64 v[212:215], v36 offset0:208 offset1:212
	ds_read2_b64 v[216:219], v36 offset0:216 offset1:220
	ds_read2_b64 v[220:223], v36 offset0:224 offset1:228
	s_nop 0
	s_waitcnt lgkmcnt(4)
	v_mfma_f32_16x16x32_bf16 v[28:31], v[204:207], v[18:21], 0
	s_waitcnt lgkmcnt(3)
	v_mfma_f32_16x16x32_bf16 v[28:31], v[208:211], v[14:17], v[28:31]
	s_nop 0
	s_waitcnt lgkmcnt(2)
	v_mfma_f32_16x16x32_bf16 v[28:31], v[212:215], v[10:13], v[28:31]
	s_nop 0
	s_waitcnt lgkmcnt(1)
	v_mfma_f32_16x16x32_bf16 v[28:31], v[216:219], v[6:9], v[28:31]
	s_nop 0
	s_waitcnt lgkmcnt(0)
	v_mfma_f32_16x16x32_bf16 v[28:31], v[220:223], v[2:5], v[28:31]
	v_add_u32_e32 v32, 0xe000, v27
	s_nop 6
	v_mul_f32_e32 v28, v26, v28
	v_mul_f32_e32 v29, v26, v29
	v_cvt_pk_bf16_f32 v28, v28, v29
	v_mul_f32_e32 v29, v26, v30
	v_mul_f32_e32 v30, v26, v31
	v_cvt_pk_bf16_f32 v29, v29, v30
	global_store_dwordx2 v[22:23], v[28:29], off offset:192
	ds_read2_b64 v[28:31], v32 offset0:224 offset1:228
	s_waitcnt lgkmcnt(0)
	v_mfma_f32_16x16x32_bf16 v[18:21], v[28:31], v[18:21], 0
	ds_read2_b64 v[28:31], v32 offset0:232 offset1:236
	s_waitcnt lgkmcnt(0)
	v_mfma_f32_16x16x32_bf16 v[14:17], v[28:31], v[14:17], v[18:21]
	s_nop 4
	ds_read2_b64 v[18:21], v32 offset0:240 offset1:244
	s_waitcnt lgkmcnt(0)
	v_mfma_f32_16x16x32_bf16 v[10:13], v[18:21], v[10:13], v[14:17]
	s_nop 2
	ds_read2_b64 v[14:17], v32 offset0:248 offset1:252
	s_waitcnt lgkmcnt(0)
	v_mfma_f32_16x16x32_bf16 v[6:9], v[14:17], v[6:9], v[10:13]
	s_nop 2
	v_add_u32_e32 v10, 0xe800, v27
	ds_read2_b64 v[10:13], v10 offset1:4
	s_waitcnt lgkmcnt(0)
	v_mfma_f32_16x16x32_bf16 v[2:5], v[10:13], v[2:5], v[6:9]
	s_nop 7
	v_mul_f32_e32 v2, v26, v2
	v_mul_f32_e32 v3, v26, v3
	v_cvt_pk_bf16_f32 v2, v2, v3
	v_mul_f32_e32 v3, v26, v4
	v_mul_f32_e32 v4, v26, v5
	v_cvt_pk_bf16_f32 v3, v3, v4
	global_store_dwordx2 v[22:23], v[2:3], off offset:224
	s_and_saveexec_b64 s[30:31], vcc
	s_cbranch_execz .LBB0_541
; __device__ __forceinline__ void attn_item(const Params& P, int half, int item, LAS unsigned char* lds, unsigned* ctr) {
;     ...
;     if (g == 0) LSE[(size_t)qrow * 12 + gi * 4 + hh] = (mx + __builtin_amdgcn_logf(den)) * 0.6931471805599453f;
	v_log_f32_e32 v2, v25
	v_readlane_b32 s8, v251, 33
	s_lshl_b32 s6, s2, 2
	v_readlane_b32 s9, v251, 34
	v_add_f32_e32 v2, v24, v2
	s_ashr_i32 s7, s6, 31
	v_mul_f32_e32 v4, 0x3f317218, v2
	v_mad_i64_i32 v[2:3], s[8:9], v133, 48, s[8:9]
	v_lshl_add_u64 v[2:3], s[6:7], 2, v[2:3]
	s_lshl_b32 s20, s4, 2
	v_lshl_add_u64 v[2:3], v[2:3], 0, s[20:21]
	global_store_dword v[2:3], v4, off
